# prep: counted vmcnt(7) at item start and dt_bias/a_log preloaded per WG via s_load (off wave-0 critical path); on top of v18
# speedup vs baseline: 1.0069x; 1.0069x over previous
; #define LAS __attribute__((address_space(3)))
; __device__ __forceinline__ float fexp(float x) { return __builtin_amdgcn_exp2f(x * 1.4426950408889634f); }
; __device__ __forceinline__ float flog(float x) { return __builtin_amdgcn_logf(x) * 0.6931471805599453f; }
; #define LAUNDER_S(x) asm volatile("" : "+s"(x))
; __device__ __forceinline__ void phase_dnprep(h16* Pdn, const h16* halo, const float* bd, const float* convw, const float* a_log, const float* dt_bias,
;                              h16* Tg, h16* qkg, float* gcg, float* betag, float* s2g, LAS unsigned char* ldsl, unsigned char* ldsb) {
;     int bid = blockIdx.x; LAUNDER_S(bid);
;     const int w = __builtin_amdgcn_readfirstlane((int)threadIdx.x >> 6);
;     constexpr int RP = 384;
;     constexpr int RAWB = 67 * RP * 2;
;     h16* qn = (h16*)(ldsb + 2 * RAWB);
;     h16* kn = qn + 64 * 136;
;     float* Mm = (float*)(kn + 64 * 136);
;     float* cw = Mm + 64 * 68;
;     float* gcs = cw + 4 * 384;
;     float* bts = gcs + 64;
;     float cv[4] = {0.f, 0.f, 0.f, 0.f}, pbr = 0.f, par_ = 0.f;
;     ...
;     if (bid < 4096) PREP_FETCH(bid, 0);
;     int cur = 0;
;     for (int item = bid; item < 4096; item += gridDim.x, cur ^= 1) {
;     ...
;             const float br = pbr, ar = par_;
;             const float beta = 1.0f / (1.0f + fexp(-br));
;             const float xs = ar + dt_bias[h];
;             const float sp = (xs > 20.f) ? xs : flog(1.0f + fexp(xs));
;             float gg = -fexp(a_log[h]) * sp;
.LBB0_318:
	s_andn2_b64 vcc, exec, s[4:5]
	s_cbranch_vccnz .LBB0_430
	v_readlane_b32 s4, v253, 34
	s_lshl_b32 s0, s26, 2
	v_readlane_b32 s12, v253, 42
	v_readlane_b32 s13, v253, 43
	s_add_u32 s50, s12, s0
	v_readlane_b32 s8, v253, 38
	v_readlane_b32 s14, v253, 44
	s_addc_u32 s51, s13, 0
	v_readlane_b32 s9, v253, 39
	v_readlane_b32 s15, v253, 45
	s_add_u32 s8, s14, s0
	s_addc_u32 s9, s15, 0
	s_cmp_lt_u32 s3, 64
	s_cselect_b64 s[14:15], -1, 0
	s_bfe_u32 s0, s3, 0x20006
	s_lshl_b32 s37, s68, 3
	s_lshl_b32 s76, s0, 4
	v_readlane_b32 s16, v253, 46
	v_readlane_b32 s17, v253, 47
	s_cmpk_lt_u32 s3, 0x100
	s_cselect_b64 s[16:17], -1, 0
	s_lshl_b32 s4, s68, 6
	s_add_i32 s4, s4, 0
	s_lshl_b32 s1, s68, 4
	s_add_i32 s70, s4, 0x21a00
	v_readlane_b32 s5, v253, 35
	s_cmpk_lt_u32 s3, 0xcc0
	s_cselect_b64 s[4:5], -1, 0
	s_lshl_b32 s77, s68, 10
	v_writelane_b32 v255, s4, 18
	s_cmpk_lt_u32 s3, 0xac0
	v_readlane_b32 s6, v253, 36
	v_writelane_b32 v255, s5, 19
	s_cselect_b64 s[4:5], -1, 0
	s_add_i32 s47, s77, 0x2000
	v_writelane_b32 v255, s4, 39
	s_cmpk_lt_u32 s3, 0x8c0
	v_readlane_b32 s6, v254, 39
	v_writelane_b32 v255, s5, 40
	s_cselect_b64 s[4:5], -1, 0
	s_add_i32 s79, s77, 0x4000
	v_writelane_b32 v255, s4, 41
	s_cmpk_lt_u32 s3, 0x6c0
	v_readlane_b32 s18, v253, 48
	v_writelane_b32 v255, s5, 42
	s_cselect_b64 s[4:5], -1, 0
	s_add_i32 s35, s77, 0x6000
	v_writelane_b32 v255, s4, 43
	s_cmpk_lt_u32 s3, 0x4c0
	v_readlane_b32 s19, v253, 49
	v_writelane_b32 v255, s5, 44
	s_cselect_b64 s[4:5], -1, 0
	s_or_b32 s13, s77, 0x8000
	v_writelane_b32 v255, s4, 45
	s_cmpk_lt_u32 s3, 0x2c0
	s_mul_i32 s40, s68, 0x1100
	v_writelane_b32 v255, s5, 46
	s_cselect_b64 s[4:5], -1, 0
	s_add_i32 s36, s77, 0xa000
	v_writelane_b32 v255, s4, 47
	s_cmpk_lt_u32 s3, 0xc0
	s_mov_b32 s39, 0
	v_writelane_b32 v255, s5, 48
	s_cselect_b64 s[4:5], -1, 0
	v_writelane_b32 v255, s4, 49
	s_or_b32 s38, s77, 0xc000
	v_readlane_b32 s7, v253, 37
	v_writelane_b32 v255, s5, 50
	s_bfe_u32 s4, s3, 0x20008
	s_cmp_le_u32 s0, s4
	s_cselect_b64 s[28:29], -1, 0
	s_cmpk_gt_u32 s3, 0x3ff
	s_cselect_b64 s[30:31], -1, 0
	s_cmpk_lt_u32 s3, 0x400
	v_readlane_b32 s5, v254, 38
	s_cselect_b32 s94, s5, s6
	s_lshl_b32 s95, s4, 4
	s_xor_b32 s4, s4, 2
	s_cmp_le_u32 s0, s4
	s_cselect_b64 s[88:89], -1, 0
	s_cmpk_gt_u32 s3, 0x1ff
	s_cselect_b64 s[18:19], -1, 0
	s_cmpk_lt_u32 s3, 0x200
	s_cselect_b32 s96, s5, s6
	s_lshl_b32 s97, s4, 4
	s_add_i32 s41, s70, s40
	s_lshl_b32 s42, s1, 2
	v_readlane_b32 s10, v253, 40
	v_readlane_b32 s11, v253, 41
	s_bfe_u32 s32, s25, 0x30006
	v_writelane_b32 v255, s32, 56
	s_lshl_b32 s32, s32, 2
	s_xor_b32 s56, s32, 16
	s_load_dword s98, s[8:9], s32
	s_load_dword s99, s[8:9], s56
	s_waitcnt lgkmcnt(0)
	v_writelane_b32 v255, s98, 52
	v_writelane_b32 v255, s99, 53
	s_load_dword s98, s[50:51], s32
	s_load_dword s99, s[50:51], s56
	s_waitcnt lgkmcnt(0)
	v_writelane_b32 v255, s98, 54
	v_writelane_b32 v255, s99, 55
	s_waitcnt vmcnt(0)
	s_branch .LBB0_321

; __device__ __forceinline__ float fexp(float x) { return __builtin_amdgcn_exp2f(x * 1.4426950408889634f); }
; __device__ __forceinline__ float flog(float x) { return __builtin_amdgcn_logf(x) * 0.6931471805599453f; }
; #define LAUNDER_V(x) asm volatile("" : "+v"(x))
; __device__ __forceinline__ void phase_dnprep(h16* Pdn, const h16* halo, const float* bd, const float* convw, const float* a_log, const float* dt_bias,
;                              h16* Tg, h16* qkg, float* gcg, float* betag, float* s2g, LAS unsigned char* ldsl, unsigned char* ldsb) {
;     ...
;         asm volatile("s_waitcnt vmcnt(0)" ::: "memory");
;         if (n == 0 && tl < 144) { int z0 = 0; LAUNDER_V(z0); const float zf = __int_as_float(z0); *(f32x4*)(raw + tl * 8) = (f32x4){zf, zf, zf, zf}; }
; #pragma unroll
;         for (int j = 0; j < 4; ++j) if (tl < 384) cw[j * 384 + tl] = cv[j];
;         if (w == 0) {
;             const float br = pbr, ar = par_;
;             const float beta = 1.0f / (1.0f + fexp(-br));
;             const float xs = ar + dt_bias[h];
;             const float sp = (xs > 20.f) ? xs : flog(1.0f + fexp(xs));
;             float gg = -fexp(a_log[h]) * sp;
; #pragma unroll
;             for (int o = 1; o < 64; o <<= 1) { const float t = __int_as_float(__builtin_amdgcn_ds_bpermute(((lane >= o) ? (lane - o) : lane) << 2, __float_as_int(gg))); if (lane >= o) gg += t; }
;             gcs[lane] = gg; bts[lane] = beta;
;             {
;                 const float eg = fexp(gg), glast = __int_as_float(__builtin_amdgcn_readlane(__float_as_int(gg), 63));
;                 gst(gcg + bh0 + lane, eg); gst(betag + bh0 + lane, beta * eg); gst(s2g + bh0 + lane, fexp(glast - gg));
;             }
;         }
.LBB0_321:
	s_mul_i32 s0, s39, 0xc900
	s_and_b32 s4, s25, 63
	v_mov_b32_e32 v82, v192
	s_add_i32 s78, s0, 0
	s_waitcnt vmcnt(7)
	s_cmp_eq_u32 s4, 0
	s_movk_i32 s3, 0x90
	s_cselect_b64 s[0:1], -1, 0
	v_cmp_gt_i32_e32 vcc, s3, v82
	s_and_b64 s[6:7], s[0:1], vcc
	s_and_saveexec_b64 s[0:1], s[6:7]
	s_cbranch_execz .LBB0_323
	v_mov_b32_e32 v0, v33
	v_lshl_add_u32 v4, v82, 4, s78
	v_mov_b32_e32 v1, v0
	v_mov_b32_e32 v2, v0
	v_mov_b32_e32 v3, v0
	ds_write_b128 v4, v[0:3]
.LBB0_323:
	s_or_b64 exec, exec, s[0:1]
	s_movk_i32 s0, 0x180
	v_cmp_gt_i32_e32 vcc, s0, v82
	s_and_saveexec_b64 s[0:1], vcc
	s_cbranch_execz .LBB0_325
	v_lshl_add_u32 v0, v82, 2, 0
	v_add_u32_e32 v0, 0x25e00, v0
	s_waitcnt vmcnt(7)
	ds_write2st64_b32 v0, v85, v89 offset1:6
	ds_write2st64_b32 v0, v95, v94 offset0:12 offset1:18
.LBB0_325:
	s_or_b64 exec, exec, s[0:1]
	s_ashr_i32 s20, s25, 9
	s_bfe_u32 s3, s25, 0x30006
	s_lshl_b32 s0, s20, 15
	s_lshl_b32 s1, s3, 12
	v_cndmask_b32_e64 v0, 0, 1, s[14:15]
	v_and_b32_e32 v99, 63, v82
	s_lshl_b32 s21, s4, 6
	s_or_b32 s0, s1, s0
	v_cmp_ne_u32_e64 s[4:5], 1, v0
	v_lshlrev_b32_e32 v0, 2, v82
	s_or_b32 s26, s0, s21
	s_andn2_b64 vcc, exec, s[14:15]
	v_lshlrev_b32_e32 v4, 2, v99
	v_cmp_gt_u32_e64 s[6:7], 16, v99
	v_and_b32_e32 v98, 0x7c, v0
	s_cbranch_vccnz .LBB0_327
	v_readlane_b32 s0, v255, 56
	s_nop 3
	s_xor_b32 s0, s0, s3
	s_bfe_u32 s0, s0, 0x10002
	s_add_i32 s1, s0, 52
	s_add_i32 s0, s0, 54
	s_nop 3
	v_readlane_b32 s1, v255, s1
	v_readlane_b32 s0, v255, s0
	s_nop 3
	v_mov_b32_e32 v2, s1
	v_mov_b32_e32 v1, s0
	s_mov_b32 s0, 0x41a00000
	v_mul_f32_e32 v0, 0xbfb8aa3b, v96
	v_exp_f32_e32 v0, v0
	v_readlane_b32 s60, v254, 43
	v_readlane_b32 s69, v254, 52
	s_mov_b32 s27, s69
	v_add_f32_e32 v0, 1.0, v0
	v_readlane_b32 s61, v254, 44
	v_readlane_b32 s62, v254, 45
	v_readlane_b32 s63, v254, 46
	v_readlane_b32 s64, v254, 47
	v_readlane_b32 s65, v254, 48
	v_readlane_b32 s66, v254, 49
	v_readlane_b32 s67, v254, 50
	v_readlane_b32 s68, v254, 51
	v_readlane_b32 s70, v254, 53
	v_readlane_b32 s71, v254, 54
	v_readlane_b32 s72, v254, 55
	v_readlane_b32 s73, v254, 56
	v_readlane_b32 s74, v254, 57
	v_readlane_b32 s75, v254, 58
	v_add_f32_e32 v2, v97, v2
	v_mul_f32_e32 v3, 0x3fb8aa3b, v2
	v_exp_f32_e32 v3, v3
	v_mul_f32_e32 v1, 0x3fb8aa3b, v1
	v_exp_f32_e32 v1, v1
	v_cmp_lt_f32_e32 vcc, s0, v2
	v_add_f32_e32 v3, 1.0, v3
	v_log_f32_e32 v3, v3
	s_nop 0
	v_mul_f32_e32 v3, 0x3f317218, v3
	v_cndmask_b32_e32 v2, v3, v2, vcc
	v_cmp_ne_u32_e32 vcc, 0, v99
	v_mul_f32_e64 v3, v2, -v1
	s_nop 0
	v_subbrev_co_u32_e64 v5, s[0:1], 0, v99, vcc
	v_lshlrev_b32_e32 v5, 2, v5
	ds_bpermute_b32 v5, v5, v3
	s_waitcnt lgkmcnt(0)
	v_fma_f32 v1, v2, -v1, v5
	v_cndmask_b32_e32 v1, v3, v1, vcc
	v_cmp_gt_u32_e32 vcc, 2, v99
	s_nop 1
	v_cndmask_b32_e64 v2, -2, 0, vcc
	v_add_lshl_u32 v2, v2, v99, 2
	ds_bpermute_b32 v2, v2, v1
	s_waitcnt lgkmcnt(0)
	v_add_f32_e32 v2, v1, v2
	v_cndmask_b32_e32 v1, v2, v1, vcc
	v_cmp_gt_u32_e32 vcc, 4, v99
	s_nop 1
	v_cndmask_b32_e64 v2, -4, 0, vcc
	v_add_lshl_u32 v2, v2, v99, 2
	ds_bpermute_b32 v2, v2, v1
	s_waitcnt lgkmcnt(0)
	v_add_f32_e32 v2, v1, v2
	v_cndmask_b32_e32 v1, v2, v1, vcc
	v_cmp_gt_u32_e32 vcc, 8, v99
	s_nop 1
	v_cndmask_b32_e64 v2, -8, 0, vcc
	v_add_lshl_u32 v2, v2, v99, 2
	ds_bpermute_b32 v2, v2, v1
	s_waitcnt lgkmcnt(0)
	v_add_f32_e32 v2, v1, v2
	v_cndmask_b32_e32 v1, v2, v1, vcc
	v_cndmask_b32_e64 v2, -16, 0, s[6:7]
	v_add_lshl_u32 v2, v2, v99, 2
	ds_bpermute_b32 v2, v2, v1
	v_cmp_gt_u32_e32 vcc, 32, v99
	s_waitcnt lgkmcnt(0)
	v_add_f32_e32 v2, v1, v2
	v_cndmask_b32_e64 v1, v2, v1, s[6:7]
	ds_bpermute_b32 v2, v98, v1
	v_readlane_b32 s7, v255, 36
	s_waitcnt lgkmcnt(0)
	v_add_f32_e32 v2, v1, v2
	v_cndmask_b32_e32 v1, v2, v1, vcc
	v_div_scale_f32 v2, s[0:1], v0, v0, 1.0
	v_rcp_f32_e32 v3, v2
	s_lshl_b64 s[0:1], s[26:27], 2
	s_add_u32 s10, s80, s0
	s_addc_u32 s11, s81, s1
	v_fma_f32 v5, -v2, v3, 1.0
	v_fmac_f32_e32 v3, v5, v3
	v_div_scale_f32 v5, vcc, 1.0, v0, 1.0
	v_mul_f32_e32 v6, v5, v3
	v_fma_f32 v7, -v2, v6, v5
	v_fmac_f32_e32 v6, v7, v3
	v_fma_f32 v2, -v2, v6, v5
	v_div_fmas_f32 v2, v2, v3, v6
	v_div_fixup_f32 v0, v2, v0, 1.0
	v_add_u32_e32 v2, 0, v4
	v_add_u32_e32 v3, 0x27600, v2
	v_add_u32_e32 v2, 0x27700, v2
	ds_write_b32 v2, v0
	v_mul_f32_e32 v2, 0x3fb8aa3b, v1
	v_exp_f32_e32 v2, v2
	v_readlane_b32 s6, v1, 63
	ds_write_b32 v3, v1
	global_store_dword v4, v2, s[10:11]
	s_add_u32 s10, s7, s0
	v_readlane_b32 s7, v255, 38
	s_addc_u32 s11, s7, s1
	v_mul_f32_e32 v0, v0, v2
	global_store_dword v4, v0, s[10:11]
	v_sub_f32_e32 v0, s6, v1
	v_mul_f32_e32 v0, 0x3fb8aa3b, v0
	v_exp_f32_e32 v0, v0
	v_readlane_b32 s7, v255, 32
	s_add_u32 s0, s7, s0
	v_readlane_b32 s7, v255, 35
	s_addc_u32 s1, s7, s1
	global_store_dword v4, v0, s[0:1]
